# GEMM epilogue stores (P1 proj, P5 xb/out) write-through sc1 to avoid L2 pollution
# baseline (speedup 1.0000x reference)
.LBB0_130:
	v_lshl_add_u32 v156, s63, 8, v176
	v_ashrrev_i32_e32 v157, 31, v156
	v_lshl_add_u64 v[164:165], v[156:157], 3, s[10:11]
	global_load_dwordx2 v[166:167], v[164:165], off
	global_load_dwordx2 v[174:175], v[164:165], off offset:128
	global_load_dwordx2 v[162:163], v[164:165], off offset:256
	global_load_dwordx2 v[160:161], v[164:165], off offset:384
	global_load_dwordx2 v[158:159], v[164:165], off offset:1024
	global_load_dwordx2 v[172:173], v[164:165], off offset:1152
	global_load_dwordx2 v[170:171], v[164:165], off offset:1280
	global_load_dwordx2 v[168:169], v[164:165], off offset:1408
	s_waitcnt vmcnt(0)
	v_or_b32_e32 v154, 16, v156
	v_ffbh_u32_e32 v164, v167
	v_min_u32_e32 v178, 32, v164
	v_lshlrev_b64 v[164:165], v178, v[166:167]
	v_min_u32_e32 v164, 1, v164
	v_or_b32_e32 v164, v165, v164
	v_cvt_f32_u32_e32 v164, v164
	v_sub_u32_e32 v165, 32, v178
	v_or_b32_e32 v152, 32, v156
	v_or_b32_e32 v150, 48, v156
	v_ldexp_f32 v164, v164, v165
	v_fmamk_f32 v164, v164, 0x30000000, v195
	v_cmp_gt_f32_e32 vcc, s2, v164
	v_mul_f32_e32 v165, 0x4b800000, v164
	v_add_u32_e32 v148, 0x80, v156
	v_cndmask_b32_e32 v164, v164, v165, vcc
	v_rsq_f32_e32 v164, v164
	v_add_u32_e32 v146, 0x90, v156
	v_add_u32_e32 v144, 0xa0, v156
	v_add_u32_e32 v142, 0xb0, v156
	v_mul_f32_e32 v165, 0x45800000, v164
	v_cndmask_b32_e32 v166, v164, v165, vcc
	v_ffbh_u32_e32 v164, v175
	v_min_u32_e32 v167, 32, v164
	v_lshlrev_b64 v[164:165], v167, v[174:175]
	v_min_u32_e32 v164, 1, v164
	v_or_b32_e32 v164, v165, v164
	v_cvt_f32_u32_e32 v164, v164
	v_sub_u32_e32 v165, 32, v167
	v_ashrrev_i32_e32 v155, 31, v154
	v_ashrrev_i32_e32 v153, 31, v152
	v_ldexp_f32 v164, v164, v165
	v_fmamk_f32 v164, v164, 0x30000000, v195
	v_cmp_gt_f32_e32 vcc, s2, v164
	v_mul_f32_e32 v165, 0x4b800000, v164
	v_ashrrev_i32_e32 v151, 31, v150
	v_cndmask_b32_e32 v164, v164, v165, vcc
	v_rsq_f32_e32 v164, v164
	v_ashrrev_i32_e32 v149, 31, v148
	v_ashrrev_i32_e32 v147, 31, v146
	v_ashrrev_i32_e32 v145, 31, v144
	v_mul_f32_e32 v165, 0x45800000, v164
	v_cndmask_b32_e32 v164, v164, v165, vcc
	v_ffbh_u32_e32 v165, v163
	v_min_u32_e32 v165, 32, v165
	v_lshlrev_b64 v[162:163], v165, v[162:163]
	v_min_u32_e32 v162, 1, v162
	v_or_b32_e32 v162, v163, v162
	v_cvt_f32_u32_e32 v162, v162
	v_sub_u32_e32 v163, 32, v165
	v_ashrrev_i32_e32 v143, 31, v142
	s_mov_b64 s[46:47], -1
	v_ldexp_f32 v162, v162, v163
	v_fmamk_f32 v162, v162, 0x30000000, v195
	v_cmp_gt_f32_e32 vcc, s2, v162
	v_mul_f32_e32 v163, 0x4b800000, v162
	s_cmp_gt_i32 s62, 28
	v_cndmask_b32_e32 v162, v162, v163, vcc
	v_rsq_f32_e32 v162, v162
	s_nop 0
	v_mul_f32_e32 v163, 0x45800000, v162
	v_cndmask_b32_e32 v162, v162, v163, vcc
	v_ffbh_u32_e32 v163, v161
	v_min_u32_e32 v163, 32, v163
	v_lshlrev_b64 v[160:161], v163, v[160:161]
	v_min_u32_e32 v160, 1, v160
	v_or_b32_e32 v160, v161, v160
	v_cvt_f32_u32_e32 v160, v160
	v_sub_u32_e32 v161, 32, v163
	v_ldexp_f32 v160, v160, v161
	v_fmamk_f32 v160, v160, 0x30000000, v195
	v_cmp_gt_f32_e32 vcc, s2, v160
	v_mul_f32_e32 v161, 0x4b800000, v160
	s_nop 0
	v_cndmask_b32_e32 v160, v160, v161, vcc
	v_rsq_f32_e32 v160, v160
	s_nop 0
	v_mul_f32_e32 v161, 0x45800000, v160
	v_cndmask_b32_e32 v160, v160, v161, vcc
	v_ffbh_u32_e32 v161, v159
	v_min_u32_e32 v161, 32, v161
	v_lshlrev_b64 v[158:159], v161, v[158:159]
	v_min_u32_e32 v158, 1, v158
	v_or_b32_e32 v158, v159, v158
	v_cvt_f32_u32_e32 v158, v158
	v_sub_u32_e32 v159, 32, v161
	v_ldexp_f32 v158, v158, v159
	v_fmamk_f32 v158, v158, 0x30000000, v195
	v_cmp_gt_f32_e32 vcc, s2, v158
	v_mul_f32_e32 v159, 0x4b800000, v158
	s_nop 0
	v_cndmask_b32_e32 v158, v158, v159, vcc
	v_rsq_f32_e32 v158, v158
	s_nop 0
	v_mul_f32_e32 v159, 0x45800000, v158
	v_cndmask_b32_e32 v158, v158, v159, vcc
	v_ffbh_u32_e32 v159, v173
	v_min_u32_e32 v159, 32, v159
	v_lshlrev_b64 v[172:173], v159, v[172:173]
	v_min_u32_e32 v161, 1, v172
	v_or_b32_e32 v161, v173, v161
	v_cvt_f32_u32_e32 v161, v161
	v_sub_u32_e32 v159, 32, v159
	v_ldexp_f32 v159, v161, v159
	v_fmamk_f32 v159, v159, 0x30000000, v195
	v_cmp_gt_f32_e32 vcc, s2, v159
	v_mul_f32_e32 v161, 0x4b800000, v159
	s_nop 0
	v_cndmask_b32_e32 v159, v159, v161, vcc
	v_rsq_f32_e32 v159, v159
	s_nop 0
	v_mul_f32_e32 v161, 0x45800000, v159
	v_cndmask_b32_e32 v172, v159, v161, vcc
	v_ffbh_u32_e32 v159, v171
	v_min_u32_e32 v159, 32, v159
	v_lshlrev_b64 v[170:171], v159, v[170:171]
	v_min_u32_e32 v161, 1, v170
	v_or_b32_e32 v161, v171, v161
	v_cvt_f32_u32_e32 v161, v161
	v_sub_u32_e32 v159, 32, v159
	v_ldexp_f32 v159, v161, v159
	v_fmamk_f32 v159, v159, 0x30000000, v195
	v_cmp_gt_f32_e32 vcc, s2, v159
	v_mul_f32_e32 v161, 0x4b800000, v159
	s_nop 0
	v_cndmask_b32_e32 v159, v159, v161, vcc
	v_rsq_f32_e32 v159, v159
	s_nop 0
	v_mul_f32_e32 v161, 0x45800000, v159
	v_cndmask_b32_e32 v170, v159, v161, vcc
	v_ffbh_u32_e32 v159, v169
	v_min_u32_e32 v159, 32, v159
	v_lshlrev_b64 v[168:169], v159, v[168:169]
	v_min_u32_e32 v161, 1, v168
	v_or_b32_e32 v161, v169, v161
	v_cvt_f32_u32_e32 v161, v161
	v_sub_u32_e32 v159, 32, v159
	v_ldexp_f32 v159, v161, v159
	v_fmamk_f32 v159, v159, 0x30000000, v195
	v_cmp_gt_f32_e32 vcc, s2, v159
	v_mul_f32_e32 v161, 0x4b800000, v159
	s_nop 0
	v_cndmask_b32_e32 v159, v159, v161, vcc
	v_rsq_f32_e32 v159, v159
	s_nop 0
	v_mul_f32_e32 v161, 0x45800000, v159
	v_cndmask_b32_e32 v168, v159, v161, vcc
	s_cbranch_scc0 .LBB0_134
	s_andn2_b64 vcc, exec, s[26:27]
	s_cbranch_vccnz .LBB0_133
	v_lshlrev_b64 v[174:175], 7, v[156:157]
	v_lshl_add_u64 v[174:175], v[136:137], 0, v[174:175]
	v_pk_mul_f32 v[180:181], v[128:129], v[166:167] op_sel_hi:[1,0]
	v_pk_mul_f32 v[178:179], v[126:127], v[166:167] op_sel_hi:[1,0]
	global_store_dwordx4 v[174:175], v[178:181], off sc1
	s_nop 1
	v_pk_mul_f32 v[180:181], v[124:125], v[166:167] op_sel_hi:[1,0]
	v_pk_mul_f32 v[178:179], v[122:123], v[166:167] op_sel_hi:[1,0]
	global_store_dwordx4 v[174:175], v[178:181], off offset:16 sc1
	v_lshlrev_b64 v[174:175], 7, v[154:155]
	v_lshl_add_u64 v[174:175], v[136:137], 0, v[174:175]
	v_pk_mul_f32 v[180:181], v[112:113], v[164:165] op_sel_hi:[1,0]
	v_pk_mul_f32 v[178:179], v[110:111], v[164:165] op_sel_hi:[1,0]
	global_store_dwordx4 v[174:175], v[178:181], off sc1
	s_nop 1
	v_pk_mul_f32 v[180:181], v[108:109], v[164:165] op_sel_hi:[1,0]
	v_pk_mul_f32 v[178:179], v[106:107], v[164:165] op_sel_hi:[1,0]
	global_store_dwordx4 v[174:175], v[178:181], off offset:16 sc1
	v_lshlrev_b64 v[174:175], 7, v[152:153]
	v_lshl_add_u64 v[174:175], v[136:137], 0, v[174:175]
	v_pk_mul_f32 v[180:181], v[96:97], v[162:163] op_sel_hi:[1,0]
	v_pk_mul_f32 v[178:179], v[94:95], v[162:163] op_sel_hi:[1,0]
	global_store_dwordx4 v[174:175], v[178:181], off sc1
	s_nop 1
	v_pk_mul_f32 v[180:181], v[92:93], v[162:163] op_sel_hi:[1,0]
	v_pk_mul_f32 v[178:179], v[90:91], v[162:163] op_sel_hi:[1,0]
	global_store_dwordx4 v[174:175], v[178:181], off offset:16 sc1
	v_lshlrev_b64 v[174:175], 7, v[150:151]
	v_lshl_add_u64 v[174:175], v[136:137], 0, v[174:175]
	v_pk_mul_f32 v[180:181], v[80:81], v[160:161] op_sel_hi:[1,0]
	v_pk_mul_f32 v[178:179], v[78:79], v[160:161] op_sel_hi:[1,0]
	global_store_dwordx4 v[174:175], v[178:181], off sc1
	s_nop 1
	v_pk_mul_f32 v[180:181], v[76:77], v[160:161] op_sel_hi:[1,0]
	v_pk_mul_f32 v[178:179], v[74:75], v[160:161] op_sel_hi:[1,0]
	global_store_dwordx4 v[174:175], v[178:181], off offset:16 sc1
	v_lshlrev_b64 v[174:175], 7, v[148:149]
	v_lshl_add_u64 v[174:175], v[136:137], 0, v[174:175]
	v_pk_mul_f32 v[180:181], v[64:65], v[158:159] op_sel_hi:[1,0]
	v_pk_mul_f32 v[178:179], v[62:63], v[158:159] op_sel_hi:[1,0]
	global_store_dwordx4 v[174:175], v[178:181], off sc1
	s_nop 1
	v_pk_mul_f32 v[180:181], v[60:61], v[158:159] op_sel_hi:[1,0]
	v_pk_mul_f32 v[178:179], v[58:59], v[158:159] op_sel_hi:[1,0]
	global_store_dwordx4 v[174:175], v[178:181], off offset:16 sc1
	v_lshlrev_b64 v[174:175], 7, v[146:147]
	v_lshl_add_u64 v[174:175], v[136:137], 0, v[174:175]
	v_pk_mul_f32 v[180:181], v[48:49], v[172:173] op_sel_hi:[1,0]
	v_pk_mul_f32 v[178:179], v[46:47], v[172:173] op_sel_hi:[1,0]
	global_store_dwordx4 v[174:175], v[178:181], off sc1
	s_nop 1
	v_pk_mul_f32 v[180:181], v[44:45], v[172:173] op_sel_hi:[1,0]
	v_pk_mul_f32 v[178:179], v[42:43], v[172:173] op_sel_hi:[1,0]
	global_store_dwordx4 v[174:175], v[178:181], off offset:16 sc1
	v_lshlrev_b64 v[174:175], 7, v[144:145]
	v_lshl_add_u64 v[174:175], v[136:137], 0, v[174:175]
	v_pk_mul_f32 v[180:181], v[32:33], v[170:171] op_sel_hi:[1,0]
	v_pk_mul_f32 v[178:179], v[30:31], v[170:171] op_sel_hi:[1,0]
	global_store_dwordx4 v[174:175], v[178:181], off sc1
	s_nop 1
	v_pk_mul_f32 v[180:181], v[28:29], v[170:171] op_sel_hi:[1,0]
	v_pk_mul_f32 v[178:179], v[26:27], v[170:171] op_sel_hi:[1,0]
	global_store_dwordx4 v[174:175], v[178:181], off offset:16 sc1
	v_lshlrev_b64 v[174:175], 7, v[142:143]
	v_lshl_add_u64 v[174:175], v[136:137], 0, v[174:175]
	v_pk_mul_f32 v[180:181], v[16:17], v[168:169] op_sel_hi:[1,0]
	v_pk_mul_f32 v[178:179], v[14:15], v[168:169] op_sel_hi:[1,0]
	global_store_dwordx4 v[174:175], v[178:181], off sc1
	s_nop 1
	v_pk_mul_f32 v[180:181], v[12:13], v[168:169] op_sel_hi:[1,0]
	v_pk_mul_f32 v[178:179], v[10:11], v[168:169] op_sel_hi:[1,0]
	global_store_dwordx4 v[174:175], v[178:181], off offset:16 sc1

.LBB0_134:
	s_andn2_b64 vcc, exec, s[46:47]
	s_cbranch_vccnz .LBB0_171
	s_cmp_lt_i32 s62, 6
	s_cselect_b64 s[46:47], -1, 0
	s_and_b32 s39, s62, -4
	s_cmp_eq_u32 s39, 12
	s_cselect_b64 s[48:49], -1, 0
	s_or_b64 s[50:51], s[46:47], s[48:49]
	v_lshl_or_b32 v174, s62, 8, v193
	s_mov_b64 s[48:49], -1
	s_and_b64 vcc, exec, s[50:51]
	s_cbranch_vccnz .LBB0_137
	v_mov_b32_e32 v175, v1
	v_mov_b64_e32 v[178:179], s[0:1]
	v_mad_i64_i32 v[202:203], s[48:49], v156, s35, v[178:179]
	v_lshlrev_b64 v[180:181], 1, v[174:175]
	v_pk_mul_f32 v[210:211], v[128:129], v[166:167] op_sel_hi:[1,0]
	v_pk_mul_f32 v[208:209], v[126:127], v[166:167] op_sel_hi:[1,0]
	v_lshl_add_u64 v[202:203], v[202:203], 0, v[180:181]
	v_pk_mul_f32 v[212:213], v[124:125], v[166:167] op_sel_hi:[1,0]
	v_pk_mul_f32 v[214:215], v[122:123], v[166:167] op_sel_hi:[1,0]
	v_cvt_pk_bf16_f32 v208, v208, v209
	v_cvt_pk_bf16_f32 v209, v210, v211
	s_nop 0
	v_cvt_pk_bf16_f32 v210, v214, v215
	v_cvt_pk_bf16_f32 v211, v212, v213
	global_store_dwordx4 v[202:203], v[208:211], off sc1
	v_pk_mul_f32 v[212:213], v[116:117], v[166:167] op_sel_hi:[1,0]
	v_pk_mul_f32 v[214:215], v[114:115], v[166:167] op_sel_hi:[1,0]
	v_pk_mul_f32 v[210:211], v[120:121], v[166:167] op_sel_hi:[1,0]
	v_pk_mul_f32 v[208:209], v[118:119], v[166:167] op_sel_hi:[1,0]
	s_nop 0
	v_cvt_pk_bf16_f32 v208, v208, v209
	v_cvt_pk_bf16_f32 v209, v210, v211
	v_cvt_pk_bf16_f32 v210, v214, v215
	v_cvt_pk_bf16_f32 v211, v212, v213
	global_store_dwordx4 v[202:203], v[208:211], off offset:256 sc1
	v_mad_i64_i32 v[202:203], s[48:49], v154, s35, v[178:179]
	s_nop 0
	v_pk_mul_f32 v[210:211], v[112:113], v[164:165] op_sel_hi:[1,0]
	v_pk_mul_f32 v[208:209], v[110:111], v[164:165] op_sel_hi:[1,0]
	v_lshl_add_u64 v[202:203], v[202:203], 0, v[180:181]
	v_pk_mul_f32 v[212:213], v[108:109], v[164:165] op_sel_hi:[1,0]
	v_pk_mul_f32 v[214:215], v[106:107], v[164:165] op_sel_hi:[1,0]
	v_cvt_pk_bf16_f32 v208, v208, v209
	v_cvt_pk_bf16_f32 v209, v210, v211
	s_nop 0
	v_cvt_pk_bf16_f32 v210, v214, v215
	v_cvt_pk_bf16_f32 v211, v212, v213
	global_store_dwordx4 v[202:203], v[208:211], off sc1
	v_pk_mul_f32 v[212:213], v[100:101], v[164:165] op_sel_hi:[1,0]
	v_pk_mul_f32 v[214:215], v[98:99], v[164:165] op_sel_hi:[1,0]
	v_pk_mul_f32 v[210:211], v[104:105], v[164:165] op_sel_hi:[1,0]
	v_pk_mul_f32 v[208:209], v[102:103], v[164:165] op_sel_hi:[1,0]
	s_nop 0
	v_cvt_pk_bf16_f32 v208, v208, v209
	v_cvt_pk_bf16_f32 v209, v210, v211
	v_cvt_pk_bf16_f32 v210, v214, v215
	v_cvt_pk_bf16_f32 v211, v212, v213
	global_store_dwordx4 v[202:203], v[208:211], off offset:256 sc1
	v_mad_i64_i32 v[202:203], s[48:49], v152, s35, v[178:179]
	s_nop 0
	v_pk_mul_f32 v[210:211], v[96:97], v[162:163] op_sel_hi:[1,0]
	v_pk_mul_f32 v[208:209], v[94:95], v[162:163] op_sel_hi:[1,0]
	v_lshl_add_u64 v[202:203], v[202:203], 0, v[180:181]
	v_pk_mul_f32 v[212:213], v[92:93], v[162:163] op_sel_hi:[1,0]
	v_pk_mul_f32 v[214:215], v[90:91], v[162:163] op_sel_hi:[1,0]
	v_cvt_pk_bf16_f32 v208, v208, v209
	v_cvt_pk_bf16_f32 v209, v210, v211
	s_nop 0
	v_cvt_pk_bf16_f32 v210, v214, v215
	v_cvt_pk_bf16_f32 v211, v212, v213
	global_store_dwordx4 v[202:203], v[208:211], off sc1
	v_pk_mul_f32 v[212:213], v[84:85], v[162:163] op_sel_hi:[1,0]
	v_pk_mul_f32 v[214:215], v[82:83], v[162:163] op_sel_hi:[1,0]
	v_pk_mul_f32 v[210:211], v[88:89], v[162:163] op_sel_hi:[1,0]
	v_pk_mul_f32 v[208:209], v[86:87], v[162:163] op_sel_hi:[1,0]
	s_nop 0
	v_cvt_pk_bf16_f32 v208, v208, v209
	v_cvt_pk_bf16_f32 v209, v210, v211
	v_cvt_pk_bf16_f32 v210, v214, v215
	v_cvt_pk_bf16_f32 v211, v212, v213
	global_store_dwordx4 v[202:203], v[208:211], off offset:256 sc1
	v_mad_i64_i32 v[202:203], s[48:49], v150, s35, v[178:179]
	s_nop 0
	v_pk_mul_f32 v[210:211], v[80:81], v[160:161] op_sel_hi:[1,0]
	v_pk_mul_f32 v[208:209], v[78:79], v[160:161] op_sel_hi:[1,0]
	v_lshl_add_u64 v[202:203], v[202:203], 0, v[180:181]
	v_pk_mul_f32 v[212:213], v[76:77], v[160:161] op_sel_hi:[1,0]
	v_pk_mul_f32 v[214:215], v[74:75], v[160:161] op_sel_hi:[1,0]
	v_cvt_pk_bf16_f32 v208, v208, v209
	v_cvt_pk_bf16_f32 v209, v210, v211
	s_nop 0
	v_cvt_pk_bf16_f32 v210, v214, v215
	v_cvt_pk_bf16_f32 v211, v212, v213
	global_store_dwordx4 v[202:203], v[208:211], off sc1
	v_pk_mul_f32 v[212:213], v[68:69], v[160:161] op_sel_hi:[1,0]
	v_pk_mul_f32 v[214:215], v[66:67], v[160:161] op_sel_hi:[1,0]
	v_pk_mul_f32 v[210:211], v[72:73], v[160:161] op_sel_hi:[1,0]
	v_pk_mul_f32 v[208:209], v[70:71], v[160:161] op_sel_hi:[1,0]
	s_nop 0
	v_cvt_pk_bf16_f32 v208, v208, v209
	v_cvt_pk_bf16_f32 v209, v210, v211
	v_cvt_pk_bf16_f32 v210, v214, v215
	v_cvt_pk_bf16_f32 v211, v212, v213
	global_store_dwordx4 v[202:203], v[208:211], off offset:256 sc1
	v_mad_i64_i32 v[202:203], s[48:49], v148, s35, v[178:179]
	s_nop 0
	v_pk_mul_f32 v[210:211], v[64:65], v[158:159] op_sel_hi:[1,0]
	v_pk_mul_f32 v[208:209], v[62:63], v[158:159] op_sel_hi:[1,0]
	v_lshl_add_u64 v[202:203], v[202:203], 0, v[180:181]
	v_pk_mul_f32 v[212:213], v[60:61], v[158:159] op_sel_hi:[1,0]
	v_pk_mul_f32 v[214:215], v[58:59], v[158:159] op_sel_hi:[1,0]
	v_cvt_pk_bf16_f32 v208, v208, v209
	v_cvt_pk_bf16_f32 v209, v210, v211
	s_nop 0
	v_cvt_pk_bf16_f32 v210, v214, v215
	v_cvt_pk_bf16_f32 v211, v212, v213
	global_store_dwordx4 v[202:203], v[208:211], off sc1
	v_pk_mul_f32 v[212:213], v[52:53], v[158:159] op_sel_hi:[1,0]
	v_pk_mul_f32 v[214:215], v[50:51], v[158:159] op_sel_hi:[1,0]
	v_pk_mul_f32 v[210:211], v[56:57], v[158:159] op_sel_hi:[1,0]
	v_pk_mul_f32 v[208:209], v[54:55], v[158:159] op_sel_hi:[1,0]
	s_nop 0
	v_cvt_pk_bf16_f32 v208, v208, v209
	v_cvt_pk_bf16_f32 v209, v210, v211
	v_cvt_pk_bf16_f32 v210, v214, v215
	v_cvt_pk_bf16_f32 v211, v212, v213
	global_store_dwordx4 v[202:203], v[208:211], off offset:256 sc1
	v_mad_i64_i32 v[202:203], s[48:49], v146, s35, v[178:179]
	s_nop 0
	v_pk_mul_f32 v[210:211], v[48:49], v[172:173] op_sel_hi:[1,0]
	v_pk_mul_f32 v[208:209], v[46:47], v[172:173] op_sel_hi:[1,0]
	v_lshl_add_u64 v[202:203], v[202:203], 0, v[180:181]
	v_pk_mul_f32 v[212:213], v[44:45], v[172:173] op_sel_hi:[1,0]
	v_pk_mul_f32 v[214:215], v[42:43], v[172:173] op_sel_hi:[1,0]
	v_cvt_pk_bf16_f32 v208, v208, v209
	v_cvt_pk_bf16_f32 v209, v210, v211
	s_nop 0
	v_cvt_pk_bf16_f32 v210, v214, v215
	v_cvt_pk_bf16_f32 v211, v212, v213
	global_store_dwordx4 v[202:203], v[208:211], off sc1
	v_pk_mul_f32 v[212:213], v[36:37], v[172:173] op_sel_hi:[1,0]
	v_pk_mul_f32 v[214:215], v[34:35], v[172:173] op_sel_hi:[1,0]
	v_pk_mul_f32 v[210:211], v[40:41], v[172:173] op_sel_hi:[1,0]
	v_pk_mul_f32 v[208:209], v[38:39], v[172:173] op_sel_hi:[1,0]
	s_nop 0
	v_cvt_pk_bf16_f32 v208, v208, v209
	v_cvt_pk_bf16_f32 v209, v210, v211
	v_cvt_pk_bf16_f32 v210, v214, v215
	v_cvt_pk_bf16_f32 v211, v212, v213
	global_store_dwordx4 v[202:203], v[208:211], off offset:256 sc1
	v_mad_i64_i32 v[202:203], s[48:49], v144, s35, v[178:179]
	s_nop 0
	v_pk_mul_f32 v[210:211], v[32:33], v[170:171] op_sel_hi:[1,0]
	v_pk_mul_f32 v[208:209], v[30:31], v[170:171] op_sel_hi:[1,0]
	v_lshl_add_u64 v[202:203], v[202:203], 0, v[180:181]
	v_pk_mul_f32 v[212:213], v[28:29], v[170:171] op_sel_hi:[1,0]
	v_pk_mul_f32 v[214:215], v[26:27], v[170:171] op_sel_hi:[1,0]
	v_cvt_pk_bf16_f32 v208, v208, v209
	v_cvt_pk_bf16_f32 v209, v210, v211
	v_mad_i64_i32 v[178:179], s[48:49], v142, s35, v[178:179]
	v_cvt_pk_bf16_f32 v210, v214, v215
	v_cvt_pk_bf16_f32 v211, v212, v213
	global_store_dwordx4 v[202:203], v[208:211], off sc1
	v_pk_mul_f32 v[212:213], v[20:21], v[170:171] op_sel_hi:[1,0]
	v_pk_mul_f32 v[214:215], v[18:19], v[170:171] op_sel_hi:[1,0]
	v_pk_mul_f32 v[210:211], v[24:25], v[170:171] op_sel_hi:[1,0]
	v_pk_mul_f32 v[208:209], v[22:23], v[170:171] op_sel_hi:[1,0]
	s_mov_b64 s[48:49], 0
	v_cvt_pk_bf16_f32 v208, v208, v209
	v_cvt_pk_bf16_f32 v209, v210, v211
	v_cvt_pk_bf16_f32 v210, v214, v215
	v_cvt_pk_bf16_f32 v211, v212, v213
	global_store_dwordx4 v[202:203], v[208:211], off offset:256 sc1
	v_lshl_add_u64 v[202:203], v[178:179], 0, v[180:181]
	v_pk_mul_f32 v[180:181], v[16:17], v[168:169] op_sel_hi:[1,0]
	v_pk_mul_f32 v[178:179], v[14:15], v[168:169] op_sel_hi:[1,0]
	v_pk_mul_f32 v[208:209], v[12:13], v[168:169] op_sel_hi:[1,0]
	v_pk_mul_f32 v[210:211], v[10:11], v[168:169] op_sel_hi:[1,0]
	v_cvt_pk_bf16_f32 v178, v178, v179
	v_cvt_pk_bf16_f32 v179, v180, v181
	s_nop 0
	v_cvt_pk_bf16_f32 v180, v210, v211
	v_cvt_pk_bf16_f32 v181, v208, v209
	global_store_dwordx4 v[202:203], v[178:181], off sc1
	v_pk_mul_f32 v[208:209], v[4:5], v[168:169] op_sel_hi:[1,0]
	v_pk_mul_f32 v[210:211], v[2:3], v[168:169] op_sel_hi:[1,0]
	v_pk_mul_f32 v[180:181], v[8:9], v[168:169] op_sel_hi:[1,0]
	v_pk_mul_f32 v[178:179], v[6:7], v[168:169] op_sel_hi:[1,0]
	s_nop 0
	v_cvt_pk_bf16_f32 v178, v178, v179
	v_cvt_pk_bf16_f32 v179, v180, v181
	v_cvt_pk_bf16_f32 v180, v210, v211
	v_cvt_pk_bf16_f32 v181, v208, v209
	global_store_dwordx4 v[202:203], v[178:181], off offset:256 sc1

.LBB0_170:
	s_or_b64 exec, exec, s[48:49]
	s_cmp_lt_i32 s62, 3
	s_cselect_b64 s[48:49], -1, 0
	s_and_b32 s39, s62, -2
	s_cmp_eq_u32 s39, 12
	s_cselect_b64 s[50:51], -1, 0
	s_or_b64 vcc, s[48:49], s[50:51]
	v_readlane_b32 s64, v252, 11
	s_and_b64 s[46:47], s[46:47], exec
	v_readlane_b32 s70, v252, 17
	v_readlane_b32 s71, v252, 18
	v_readlane_b32 s72, v252, 19
	v_readlane_b32 s73, v252, 20
	v_readlane_b32 s74, v252, 21
	v_readlane_b32 s75, v252, 22
	v_readlane_b32 s76, v252, 23
	v_readlane_b32 s77, v252, 24
	s_cselect_b32 s39, s70, s74
	s_cselect_b32 s41, s71, s75
	s_cselect_b32 s48, s72, s76
	s_cselect_b32 s49, s73, s77
	s_and_b64 s[46:47], vcc, exec
	s_cselect_b32 s39, s39, s48
	s_cselect_b32 s41, s41, s49
	s_add_u32 s39, s39, s36
	s_addc_u32 s41, s41, s37
	s_add_u32 s46, s39, s14
	s_waitcnt lgkmcnt(0)
	s_barrier
	s_addc_u32 s47, s41, 0
	global_load_dwordx4 v[178:181], v206, s[46:47]
	global_load_dwordx4 v[208:211], v206, s[46:47] offset:16
	ds_read_b64 v[202:203], v188
	v_mov_b32_e32 v143, 0x3e38aa3b
	v_cndmask_b32_e32 v196, 1.0, v143, vcc
	v_ashrrev_i32_e32 v175, 31, v174
	v_readlane_b32 s65, v252, 12
	s_waitcnt lgkmcnt(0)
	v_add_f32_e32 v143, v202, v203
	v_fmamk_f32 v143, v143, 0x3c800000, v195
	v_mul_f32_e32 v145, 0x4b800000, v143
	v_cmp_gt_f32_e32 vcc, s2, v143
	v_readlane_b32 s66, v252, 13
	v_readlane_b32 s67, v252, 14
	v_cndmask_b32_e32 v143, v143, v145, vcc
	v_rsq_f32_e32 v143, v143
	v_readlane_b32 s68, v252, 15
	v_readlane_b32 s69, v252, 16
	v_readlane_b32 s78, v252, 25
	v_mul_f32_e32 v145, 0x45800000, v143
	v_cndmask_b32_e32 v143, v143, v145, vcc
	v_mul_f32_e32 v202, v166, v143
	v_pk_mul_f32 v[212:213], v[126:127], v[202:203] op_sel_hi:[1,0]
	v_pk_mul_f32 v[214:215], v[128:129], v[202:203] op_sel_hi:[1,0]
	v_pk_mul_f32 v[216:217], v[122:123], v[202:203] op_sel_hi:[1,0]
	v_pk_mul_f32 v[202:203], v[124:125], v[202:203] op_sel_hi:[1,0]
	v_readlane_b32 s79, v252, 26
	s_waitcnt vmcnt(1)
	v_pk_mul_f32 v[128:129], v[196:197], v[178:179] op_sel_hi:[0,1]
	s_waitcnt vmcnt(0)
	v_pk_mul_f32 v[124:125], v[196:197], v[208:209] op_sel_hi:[0,1]
	v_pk_mul_f32 v[126:127], v[196:197], v[180:181] op_sel_hi:[0,1]
	v_pk_mul_f32 v[122:123], v[196:197], v[210:211] op_sel_hi:[0,1]
	v_pk_mul_f32 v[180:181], v[128:129], v[212:213]
	v_pk_mul_f32 v[210:211], v[124:125], v[216:217]
	v_pk_mul_f32 v[178:179], v[126:127], v[214:215]
	v_pk_mul_f32 v[202:203], v[122:123], v[202:203]
	v_cvt_pk_bf16_f32 v208, v180, v181
	v_cvt_pk_bf16_f32 v209, v178, v179
	v_cvt_pk_bf16_f32 v210, v210, v211
	v_mov_b64_e32 v[178:179], s[0:1]
	v_cvt_pk_bf16_f32 v211, v202, v203
	ds_read_b64 v[180:181], v188 offset:16
	v_mad_i64_i32 v[202:203], s[46:47], v156, s35, v[178:179]
	v_lshlrev_b64 v[156:157], 1, v[174:175]
	v_lshl_add_u64 v[174:175], v[202:203], 0, v[156:157]
	s_waitcnt lgkmcnt(0)
	v_add_f32_e32 v143, v180, v181
	v_fmamk_f32 v143, v143, 0x3c800000, v195
	v_mul_f32_e32 v145, 0x4b800000, v143
	v_cmp_gt_f32_e32 vcc, s2, v143
	global_store_dwordx4 v[174:175], v[208:211], off sc1
	s_nop 0
	v_cndmask_b32_e32 v143, v143, v145, vcc
	v_rsq_f32_e32 v143, v143
	s_nop 0
	v_mul_f32_e32 v145, 0x45800000, v143
	v_cndmask_b32_e32 v143, v143, v145, vcc
	v_mul_f32_e32 v166, v166, v143
	v_pk_mul_f32 v[118:119], v[118:119], v[166:167] op_sel_hi:[1,0]
	v_pk_mul_f32 v[114:115], v[114:115], v[166:167] op_sel_hi:[1,0]
	v_pk_mul_f32 v[116:117], v[116:117], v[166:167] op_sel_hi:[1,0]
	v_pk_mul_f32 v[120:121], v[120:121], v[166:167] op_sel_hi:[1,0]
	v_pk_mul_f32 v[118:119], v[128:129], v[118:119]
	v_pk_mul_f32 v[166:167], v[122:123], v[116:117]
	v_pk_mul_f32 v[116:117], v[124:125], v[114:115]
	v_pk_mul_f32 v[120:121], v[126:127], v[120:121]
	v_cvt_pk_bf16_f32 v114, v118, v119
	s_nop 0
	v_cvt_pk_bf16_f32 v115, v120, v121
	v_cvt_pk_bf16_f32 v116, v116, v117
	v_cvt_pk_bf16_f32 v117, v166, v167
	ds_read_b64 v[118:119], v188 offset:512
	global_store_dwordx4 v[174:175], v[114:117], off offset:256 sc1
	s_waitcnt lgkmcnt(0)
	v_add_f32_e32 v118, v118, v119
	v_fmamk_f32 v118, v118, 0x3c800000, v195
	v_mul_f32_e32 v119, 0x4b800000, v118
	v_cmp_gt_f32_e32 vcc, s2, v118
	s_nop 1
	v_cndmask_b32_e32 v118, v118, v119, vcc
	v_rsq_f32_e32 v118, v118
	s_nop 0
	v_mul_f32_e32 v114, 0x45800000, v118
	v_cndmask_b32_e32 v114, v118, v114, vcc
	v_mul_f32_e32 v114, v164, v114
	v_pk_mul_f32 v[110:111], v[110:111], v[114:115] op_sel_hi:[1,0]
	v_pk_mul_f32 v[106:107], v[106:107], v[114:115] op_sel_hi:[1,0]
	v_pk_mul_f32 v[108:109], v[108:109], v[114:115] op_sel_hi:[1,0]
	v_pk_mul_f32 v[112:113], v[112:113], v[114:115] op_sel_hi:[1,0]
	v_pk_mul_f32 v[110:111], v[128:129], v[110:111]
	v_pk_mul_f32 v[114:115], v[122:123], v[108:109]
	v_pk_mul_f32 v[108:109], v[124:125], v[106:107]
	v_pk_mul_f32 v[112:113], v[126:127], v[112:113]
	v_cvt_pk_bf16_f32 v106, v110, v111
	s_nop 0
	v_cvt_pk_bf16_f32 v107, v112, v113
	v_cvt_pk_bf16_f32 v108, v108, v109
	v_cvt_pk_bf16_f32 v109, v114, v115
	ds_read_b64 v[110:111], v188 offset:528
	s_waitcnt lgkmcnt(0)
	v_add_f32_e32 v110, v110, v111
	v_fmamk_f32 v110, v110, 0x3c800000, v195
	v_mul_f32_e32 v111, 0x4b800000, v110
	v_cmp_gt_f32_e32 vcc, s2, v110
	s_nop 1
	v_cndmask_b32_e32 v110, v110, v111, vcc
	v_rsq_f32_e32 v112, v110
	v_mad_i64_i32 v[110:111], s[46:47], v154, s35, v[178:179]
	v_lshl_add_u64 v[110:111], v[110:111], 0, v[156:157]
	global_store_dwordx4 v[110:111], v[106:109], off sc1
	s_nop 1
	v_mul_f32_e32 v106, 0x45800000, v112
	v_cndmask_b32_e32 v106, v112, v106, vcc
	v_mul_f32_e32 v106, v164, v106
	v_pk_mul_f32 v[102:103], v[102:103], v[106:107] op_sel_hi:[1,0]
	v_pk_mul_f32 v[98:99], v[98:99], v[106:107] op_sel_hi:[1,0]
	v_pk_mul_f32 v[100:101], v[100:101], v[106:107] op_sel_hi:[1,0]
	v_pk_mul_f32 v[104:105], v[104:105], v[106:107] op_sel_hi:[1,0]
	v_pk_mul_f32 v[102:103], v[128:129], v[102:103]
	v_pk_mul_f32 v[106:107], v[122:123], v[100:101]
	v_pk_mul_f32 v[100:101], v[124:125], v[98:99]
	v_pk_mul_f32 v[104:105], v[126:127], v[104:105]
	v_cvt_pk_bf16_f32 v98, v102, v103
	s_nop 0
	v_cvt_pk_bf16_f32 v99, v104, v105
	v_cvt_pk_bf16_f32 v100, v100, v101
	v_cvt_pk_bf16_f32 v101, v106, v107
	ds_read_b64 v[102:103], v188 offset:1024
	global_store_dwordx4 v[110:111], v[98:101], off offset:256 sc1
	s_waitcnt lgkmcnt(0)
	v_add_f32_e32 v102, v102, v103
	v_fmamk_f32 v102, v102, 0x3c800000, v195
	v_mul_f32_e32 v103, 0x4b800000, v102
	v_cmp_gt_f32_e32 vcc, s2, v102
	s_nop 1
	v_cndmask_b32_e32 v102, v102, v103, vcc
	v_rsq_f32_e32 v102, v102
	s_nop 0
	v_mul_f32_e32 v98, 0x45800000, v102
	v_cndmask_b32_e32 v98, v102, v98, vcc
	v_mul_f32_e32 v98, v162, v98
	v_pk_mul_f32 v[94:95], v[94:95], v[98:99] op_sel_hi:[1,0]
	v_pk_mul_f32 v[90:91], v[90:91], v[98:99] op_sel_hi:[1,0]
	v_pk_mul_f32 v[92:93], v[92:93], v[98:99] op_sel_hi:[1,0]
	v_pk_mul_f32 v[96:97], v[96:97], v[98:99] op_sel_hi:[1,0]
	v_pk_mul_f32 v[94:95], v[128:129], v[94:95]
	v_pk_mul_f32 v[98:99], v[122:123], v[92:93]
	v_pk_mul_f32 v[92:93], v[124:125], v[90:91]
	v_pk_mul_f32 v[96:97], v[126:127], v[96:97]
	v_cvt_pk_bf16_f32 v90, v94, v95
	s_nop 0
	v_cvt_pk_bf16_f32 v91, v96, v97
	v_cvt_pk_bf16_f32 v92, v92, v93
	v_cvt_pk_bf16_f32 v93, v98, v99
	ds_read_b64 v[94:95], v188 offset:1040
	s_waitcnt lgkmcnt(0)
	v_add_f32_e32 v94, v94, v95
	v_fmamk_f32 v94, v94, 0x3c800000, v195
	v_mul_f32_e32 v95, 0x4b800000, v94
	v_cmp_gt_f32_e32 vcc, s2, v94
	s_nop 1
	v_cndmask_b32_e32 v94, v94, v95, vcc
	v_rsq_f32_e32 v96, v94
	v_mad_i64_i32 v[94:95], s[46:47], v152, s35, v[178:179]
	v_lshl_add_u64 v[94:95], v[94:95], 0, v[156:157]
	global_store_dwordx4 v[94:95], v[90:93], off sc1
	s_nop 1
	v_mul_f32_e32 v90, 0x45800000, v96
	v_cndmask_b32_e32 v90, v96, v90, vcc
	v_mul_f32_e32 v90, v162, v90
	v_pk_mul_f32 v[86:87], v[86:87], v[90:91] op_sel_hi:[1,0]
	v_pk_mul_f32 v[82:83], v[82:83], v[90:91] op_sel_hi:[1,0]
	v_pk_mul_f32 v[84:85], v[84:85], v[90:91] op_sel_hi:[1,0]
	v_pk_mul_f32 v[88:89], v[88:89], v[90:91] op_sel_hi:[1,0]
	v_pk_mul_f32 v[86:87], v[128:129], v[86:87]
	v_pk_mul_f32 v[90:91], v[122:123], v[84:85]
	v_pk_mul_f32 v[84:85], v[124:125], v[82:83]
	v_pk_mul_f32 v[88:89], v[126:127], v[88:89]
	v_cvt_pk_bf16_f32 v82, v86, v87
	s_nop 0
	v_cvt_pk_bf16_f32 v83, v88, v89
	v_cvt_pk_bf16_f32 v84, v84, v85
	v_cvt_pk_bf16_f32 v85, v90, v91
	ds_read_b64 v[86:87], v188 offset:1536
	global_store_dwordx4 v[94:95], v[82:85], off offset:256 sc1
	s_waitcnt lgkmcnt(0)
	v_add_f32_e32 v86, v86, v87
	v_fmamk_f32 v86, v86, 0x3c800000, v195
	v_mul_f32_e32 v87, 0x4b800000, v86
	v_cmp_gt_f32_e32 vcc, s2, v86
	s_nop 1
	v_cndmask_b32_e32 v86, v86, v87, vcc
	v_rsq_f32_e32 v86, v86
	s_nop 0
	v_mul_f32_e32 v82, 0x45800000, v86
	v_cndmask_b32_e32 v82, v86, v82, vcc
	v_mul_f32_e32 v82, v160, v82
	v_pk_mul_f32 v[78:79], v[78:79], v[82:83] op_sel_hi:[1,0]
	v_pk_mul_f32 v[74:75], v[74:75], v[82:83] op_sel_hi:[1,0]
	v_pk_mul_f32 v[76:77], v[76:77], v[82:83] op_sel_hi:[1,0]
	v_pk_mul_f32 v[80:81], v[80:81], v[82:83] op_sel_hi:[1,0]
	v_pk_mul_f32 v[78:79], v[128:129], v[78:79]
	v_pk_mul_f32 v[82:83], v[122:123], v[76:77]
	v_pk_mul_f32 v[76:77], v[124:125], v[74:75]
	v_pk_mul_f32 v[80:81], v[126:127], v[80:81]
	v_cvt_pk_bf16_f32 v74, v78, v79
	s_nop 0
	v_cvt_pk_bf16_f32 v75, v80, v81
	v_cvt_pk_bf16_f32 v76, v76, v77
	v_cvt_pk_bf16_f32 v77, v82, v83
	ds_read_b64 v[78:79], v188 offset:1552
	s_waitcnt lgkmcnt(0)
	v_add_f32_e32 v78, v78, v79
	v_fmamk_f32 v78, v78, 0x3c800000, v195
	v_mul_f32_e32 v79, 0x4b800000, v78
	v_cmp_gt_f32_e32 vcc, s2, v78
	s_nop 1
	v_cndmask_b32_e32 v78, v78, v79, vcc
	v_rsq_f32_e32 v80, v78
	v_mad_i64_i32 v[78:79], s[46:47], v150, s35, v[178:179]
	v_lshl_add_u64 v[78:79], v[78:79], 0, v[156:157]
	global_store_dwordx4 v[78:79], v[74:77], off sc1
	s_nop 1
	v_mul_f32_e32 v74, 0x45800000, v80
	v_cndmask_b32_e32 v74, v80, v74, vcc
	v_mul_f32_e32 v74, v160, v74
	v_pk_mul_f32 v[70:71], v[70:71], v[74:75] op_sel_hi:[1,0]
	v_pk_mul_f32 v[66:67], v[66:67], v[74:75] op_sel_hi:[1,0]
	v_pk_mul_f32 v[68:69], v[68:69], v[74:75] op_sel_hi:[1,0]
	v_pk_mul_f32 v[72:73], v[72:73], v[74:75] op_sel_hi:[1,0]
	v_pk_mul_f32 v[70:71], v[128:129], v[70:71]
	v_pk_mul_f32 v[74:75], v[122:123], v[68:69]
	v_pk_mul_f32 v[68:69], v[124:125], v[66:67]
	v_pk_mul_f32 v[72:73], v[126:127], v[72:73]
	v_cvt_pk_bf16_f32 v66, v70, v71
	s_nop 0
	v_cvt_pk_bf16_f32 v67, v72, v73
	v_cvt_pk_bf16_f32 v68, v68, v69
	v_cvt_pk_bf16_f32 v69, v74, v75
	ds_read_b64 v[70:71], v189
	global_store_dwordx4 v[78:79], v[66:69], off offset:256 sc1
	s_waitcnt lgkmcnt(0)
	v_add_f32_e32 v70, v70, v71
	v_fmamk_f32 v70, v70, 0x3c800000, v195
	v_mul_f32_e32 v71, 0x4b800000, v70
	v_cmp_gt_f32_e32 vcc, s2, v70
	s_nop 1
	v_cndmask_b32_e32 v70, v70, v71, vcc
	v_rsq_f32_e32 v70, v70
	s_nop 0
	v_mul_f32_e32 v66, 0x45800000, v70
	v_cndmask_b32_e32 v66, v70, v66, vcc
	v_mul_f32_e32 v66, v158, v66
	v_pk_mul_f32 v[62:63], v[62:63], v[66:67] op_sel_hi:[1,0]
	v_pk_mul_f32 v[58:59], v[58:59], v[66:67] op_sel_hi:[1,0]
	v_pk_mul_f32 v[60:61], v[60:61], v[66:67] op_sel_hi:[1,0]
	v_pk_mul_f32 v[64:65], v[64:65], v[66:67] op_sel_hi:[1,0]
	v_pk_mul_f32 v[62:63], v[128:129], v[62:63]
	v_pk_mul_f32 v[66:67], v[122:123], v[60:61]
	v_pk_mul_f32 v[60:61], v[124:125], v[58:59]
	v_pk_mul_f32 v[64:65], v[126:127], v[64:65]
	v_cvt_pk_bf16_f32 v58, v62, v63
	s_nop 0
	v_cvt_pk_bf16_f32 v59, v64, v65
	v_cvt_pk_bf16_f32 v60, v60, v61
	v_cvt_pk_bf16_f32 v61, v66, v67
	ds_read_b64 v[62:63], v189 offset:16
	s_waitcnt lgkmcnt(0)
	v_add_f32_e32 v62, v62, v63
	v_fmamk_f32 v62, v62, 0x3c800000, v195
	v_mul_f32_e32 v63, 0x4b800000, v62
	v_cmp_gt_f32_e32 vcc, s2, v62
	s_nop 1
	v_cndmask_b32_e32 v62, v62, v63, vcc
	v_rsq_f32_e32 v64, v62
	v_mad_i64_i32 v[62:63], s[46:47], v148, s35, v[178:179]
	v_lshl_add_u64 v[62:63], v[62:63], 0, v[156:157]
	global_store_dwordx4 v[62:63], v[58:61], off sc1
	s_nop 1
	v_mul_f32_e32 v58, 0x45800000, v64
	v_cndmask_b32_e32 v58, v64, v58, vcc
	v_mul_f32_e32 v58, v158, v58
	v_pk_mul_f32 v[54:55], v[54:55], v[58:59] op_sel_hi:[1,0]
	v_pk_mul_f32 v[50:51], v[50:51], v[58:59] op_sel_hi:[1,0]
	v_pk_mul_f32 v[52:53], v[52:53], v[58:59] op_sel_hi:[1,0]
	v_pk_mul_f32 v[56:57], v[56:57], v[58:59] op_sel_hi:[1,0]
	v_pk_mul_f32 v[54:55], v[128:129], v[54:55]
	v_pk_mul_f32 v[58:59], v[122:123], v[52:53]
	v_pk_mul_f32 v[52:53], v[124:125], v[50:51]
	v_pk_mul_f32 v[56:57], v[126:127], v[56:57]
	v_cvt_pk_bf16_f32 v50, v54, v55
	s_nop 0
	v_cvt_pk_bf16_f32 v51, v56, v57
	v_cvt_pk_bf16_f32 v52, v52, v53
	v_cvt_pk_bf16_f32 v53, v58, v59
	ds_read_b64 v[54:55], v190
	global_store_dwordx4 v[62:63], v[50:53], off offset:256 sc1
	s_waitcnt lgkmcnt(0)
	v_add_f32_e32 v54, v54, v55
	v_fmamk_f32 v54, v54, 0x3c800000, v195
	v_mul_f32_e32 v55, 0x4b800000, v54
	v_cmp_gt_f32_e32 vcc, s2, v54
	s_nop 1
	v_cndmask_b32_e32 v54, v54, v55, vcc
	v_rsq_f32_e32 v54, v54
	s_nop 0
	v_mul_f32_e32 v50, 0x45800000, v54
	v_cndmask_b32_e32 v50, v54, v50, vcc
	v_mul_f32_e32 v50, v172, v50
	v_pk_mul_f32 v[46:47], v[46:47], v[50:51] op_sel_hi:[1,0]
	v_pk_mul_f32 v[42:43], v[42:43], v[50:51] op_sel_hi:[1,0]
	v_pk_mul_f32 v[44:45], v[44:45], v[50:51] op_sel_hi:[1,0]
	v_pk_mul_f32 v[48:49], v[48:49], v[50:51] op_sel_hi:[1,0]
	v_pk_mul_f32 v[46:47], v[128:129], v[46:47]
	v_pk_mul_f32 v[50:51], v[122:123], v[44:45]
	v_pk_mul_f32 v[44:45], v[124:125], v[42:43]
	v_pk_mul_f32 v[48:49], v[126:127], v[48:49]
	v_cvt_pk_bf16_f32 v42, v46, v47
	s_nop 0
	v_cvt_pk_bf16_f32 v43, v48, v49
	v_cvt_pk_bf16_f32 v44, v44, v45
	v_cvt_pk_bf16_f32 v45, v50, v51
	ds_read_b64 v[46:47], v188 offset:4624
	s_waitcnt lgkmcnt(0)
	v_add_f32_e32 v46, v46, v47
	v_fmamk_f32 v46, v46, 0x3c800000, v195
	v_mul_f32_e32 v47, 0x4b800000, v46
	v_cmp_gt_f32_e32 vcc, s2, v46
	s_nop 1
	v_cndmask_b32_e32 v46, v46, v47, vcc
	v_rsq_f32_e32 v48, v46
	v_mad_i64_i32 v[46:47], s[46:47], v146, s35, v[178:179]
	v_lshl_add_u64 v[46:47], v[46:47], 0, v[156:157]
	global_store_dwordx4 v[46:47], v[42:45], off sc1
	s_nop 1
	v_mul_f32_e32 v42, 0x45800000, v48
	v_cndmask_b32_e32 v42, v48, v42, vcc
	v_mul_f32_e32 v42, v172, v42
	v_pk_mul_f32 v[38:39], v[38:39], v[42:43] op_sel_hi:[1,0]
	v_pk_mul_f32 v[34:35], v[34:35], v[42:43] op_sel_hi:[1,0]
	v_pk_mul_f32 v[36:37], v[36:37], v[42:43] op_sel_hi:[1,0]
	v_pk_mul_f32 v[40:41], v[40:41], v[42:43] op_sel_hi:[1,0]
	v_pk_mul_f32 v[38:39], v[128:129], v[38:39]
	v_pk_mul_f32 v[42:43], v[122:123], v[36:37]
	v_pk_mul_f32 v[36:37], v[124:125], v[34:35]
	v_pk_mul_f32 v[40:41], v[126:127], v[40:41]
	v_cvt_pk_bf16_f32 v34, v38, v39
	s_nop 0
	v_cvt_pk_bf16_f32 v35, v40, v41
	v_cvt_pk_bf16_f32 v36, v36, v37
	v_cvt_pk_bf16_f32 v37, v42, v43
	ds_read_b64 v[38:39], v191
	global_store_dwordx4 v[46:47], v[34:37], off offset:256 sc1
	s_waitcnt lgkmcnt(0)
	v_add_f32_e32 v38, v38, v39
	v_fmamk_f32 v38, v38, 0x3c800000, v195
	v_mul_f32_e32 v39, 0x4b800000, v38
	v_cmp_gt_f32_e32 vcc, s2, v38
	s_nop 1
	v_cndmask_b32_e32 v38, v38, v39, vcc
	v_rsq_f32_e32 v38, v38
	s_nop 0
	v_mul_f32_e32 v34, 0x45800000, v38
	v_cndmask_b32_e32 v34, v38, v34, vcc
	v_mul_f32_e32 v34, v170, v34
	v_pk_mul_f32 v[30:31], v[30:31], v[34:35] op_sel_hi:[1,0]
	v_pk_mul_f32 v[26:27], v[26:27], v[34:35] op_sel_hi:[1,0]
	v_pk_mul_f32 v[28:29], v[28:29], v[34:35] op_sel_hi:[1,0]
	v_pk_mul_f32 v[32:33], v[32:33], v[34:35] op_sel_hi:[1,0]
	v_pk_mul_f32 v[30:31], v[128:129], v[30:31]
	v_pk_mul_f32 v[34:35], v[122:123], v[28:29]
	v_pk_mul_f32 v[28:29], v[124:125], v[26:27]
	v_pk_mul_f32 v[32:33], v[126:127], v[32:33]
	v_cvt_pk_bf16_f32 v26, v30, v31
	s_nop 0
	v_cvt_pk_bf16_f32 v27, v32, v33
	v_cvt_pk_bf16_f32 v28, v28, v29
	v_cvt_pk_bf16_f32 v29, v34, v35
	ds_read_b64 v[30:31], v188 offset:5136
	s_waitcnt lgkmcnt(0)
	v_add_f32_e32 v30, v30, v31
	v_fmamk_f32 v30, v30, 0x3c800000, v195
	v_mul_f32_e32 v31, 0x4b800000, v30
	v_cmp_gt_f32_e32 vcc, s2, v30
	s_nop 1
	v_cndmask_b32_e32 v30, v30, v31, vcc
	v_rsq_f32_e32 v32, v30
	v_mad_i64_i32 v[30:31], s[46:47], v144, s35, v[178:179]
	v_lshl_add_u64 v[30:31], v[30:31], 0, v[156:157]
	global_store_dwordx4 v[30:31], v[26:29], off sc1
	s_nop 1
	v_mul_f32_e32 v26, 0x45800000, v32
	v_cndmask_b32_e32 v26, v32, v26, vcc
	v_mul_f32_e32 v26, v170, v26
	v_pk_mul_f32 v[22:23], v[22:23], v[26:27] op_sel_hi:[1,0]
	v_pk_mul_f32 v[18:19], v[18:19], v[26:27] op_sel_hi:[1,0]
	v_pk_mul_f32 v[20:21], v[20:21], v[26:27] op_sel_hi:[1,0]
	v_pk_mul_f32 v[24:25], v[24:25], v[26:27] op_sel_hi:[1,0]
	v_pk_mul_f32 v[22:23], v[128:129], v[22:23]
	v_pk_mul_f32 v[26:27], v[122:123], v[20:21]
	v_pk_mul_f32 v[20:21], v[124:125], v[18:19]
	v_pk_mul_f32 v[24:25], v[126:127], v[24:25]
	v_cvt_pk_bf16_f32 v18, v22, v23
	s_nop 0
	v_cvt_pk_bf16_f32 v19, v24, v25
	v_cvt_pk_bf16_f32 v20, v20, v21
	v_cvt_pk_bf16_f32 v21, v26, v27
	ds_read_b64 v[22:23], v192
	global_store_dwordx4 v[30:31], v[18:21], off offset:256 sc1
	s_waitcnt lgkmcnt(0)
	v_add_f32_e32 v22, v22, v23
	v_fmamk_f32 v22, v22, 0x3c800000, v195
	v_mul_f32_e32 v23, 0x4b800000, v22
	v_cmp_gt_f32_e32 vcc, s2, v22
	s_nop 1
	v_cndmask_b32_e32 v22, v22, v23, vcc
	v_rsq_f32_e32 v22, v22
	s_nop 0
	v_mul_f32_e32 v18, 0x45800000, v22
	v_cndmask_b32_e32 v18, v22, v18, vcc
	v_mul_f32_e32 v18, v168, v18
	v_pk_mul_f32 v[14:15], v[14:15], v[18:19] op_sel_hi:[1,0]
	v_pk_mul_f32 v[10:11], v[10:11], v[18:19] op_sel_hi:[1,0]
	v_pk_mul_f32 v[12:13], v[12:13], v[18:19] op_sel_hi:[1,0]
	v_pk_mul_f32 v[16:17], v[16:17], v[18:19] op_sel_hi:[1,0]
	v_pk_mul_f32 v[14:15], v[128:129], v[14:15]
	v_pk_mul_f32 v[18:19], v[122:123], v[12:13]
	v_pk_mul_f32 v[12:13], v[124:125], v[10:11]
	v_pk_mul_f32 v[16:17], v[126:127], v[16:17]
	v_cvt_pk_bf16_f32 v10, v14, v15
	s_nop 0
	v_cvt_pk_bf16_f32 v11, v16, v17
	v_cvt_pk_bf16_f32 v12, v12, v13
	v_cvt_pk_bf16_f32 v13, v18, v19
	ds_read_b64 v[14:15], v188 offset:5648
	s_waitcnt lgkmcnt(0)
	v_add_f32_e32 v14, v14, v15
	v_fmamk_f32 v14, v14, 0x3c800000, v195
	v_mul_f32_e32 v15, 0x4b800000, v14
	v_cmp_gt_f32_e32 vcc, s2, v14
	s_nop 1
	v_cndmask_b32_e32 v14, v14, v15, vcc
	v_rsq_f32_e32 v16, v14
	v_mad_i64_i32 v[14:15], s[46:47], v142, s35, v[178:179]
	v_lshl_add_u64 v[14:15], v[14:15], 0, v[156:157]
	global_store_dwordx4 v[14:15], v[10:13], off sc1
	s_nop 1
	v_mul_f32_e32 v10, 0x45800000, v16
	v_cndmask_b32_e32 v10, v16, v10, vcc
	v_mul_f32_e32 v10, v168, v10
	v_pk_mul_f32 v[2:3], v[2:3], v[10:11] op_sel_hi:[1,0]
	v_pk_mul_f32 v[4:5], v[4:5], v[10:11] op_sel_hi:[1,0]
	v_pk_mul_f32 v[6:7], v[6:7], v[10:11] op_sel_hi:[1,0]
	v_pk_mul_f32 v[8:9], v[8:9], v[10:11] op_sel_hi:[1,0]
	v_pk_mul_f32 v[10:11], v[122:123], v[4:5]
	v_pk_mul_f32 v[4:5], v[124:125], v[2:3]
	v_pk_mul_f32 v[8:9], v[126:127], v[8:9]
	v_pk_mul_f32 v[6:7], v[128:129], v[6:7]
	s_nop 0
	v_cvt_pk_bf16_f32 v2, v6, v7
	v_cvt_pk_bf16_f32 v3, v8, v9
	v_cvt_pk_bf16_f32 v4, v4, v5
	v_cvt_pk_bf16_f32 v5, v10, v11
	global_store_dwordx4 v[14:15], v[2:5], off offset:256 sc1

.LBB0_581:
	v_lshl_add_u32 v172, s64, 8, v176
	v_lshl_or_b32 v170, s63, 8, v189
	v_ashrrev_i32_e32 v171, 31, v170
	v_ashrrev_i32_e32 v173, 31, v172
	v_lshl_add_u64 v[168:169], v[170:171], 1, s[16:17]
	v_lshlrev_b64 v[118:119], 12, v[172:173]
	v_or_b32_e32 v180, 16, v172
	v_lshl_add_u64 v[118:119], v[168:169], 0, v[118:119]
	v_ashrrev_i32_e32 v181, 31, v180
	global_load_dwordx4 v[202:205], v[118:119], off
	global_load_dwordx4 v[154:157], v[118:119], off offset:256
	v_lshlrev_b64 v[118:119], 12, v[180:181]
	v_or_b32_e32 v178, 32, v172
	v_lshl_add_u64 v[118:119], v[168:169], 0, v[118:119]
	v_ashrrev_i32_e32 v179, 31, v178
	global_load_dwordx4 v[150:153], v[118:119], off
	global_load_dwordx4 v[146:149], v[118:119], off offset:256
	v_lshlrev_b64 v[118:119], 12, v[178:179]
	v_or_b32_e32 v174, 48, v172
	v_lshl_add_u64 v[118:119], v[168:169], 0, v[118:119]
	v_ashrrev_i32_e32 v175, 31, v174
	global_load_dwordx4 v[142:145], v[118:119], off
	global_load_dwordx4 v[138:141], v[118:119], off offset:256
	v_lshlrev_b64 v[118:119], 12, v[174:175]
	v_lshl_add_u64 v[118:119], v[168:169], 0, v[118:119]
	global_load_dwordx4 v[126:129], v[118:119], off
	s_nop 0
	global_load_dwordx4 v[118:121], v[118:119], off offset:256
	v_cndmask_b32_e64 v182, 0, 1, s[38:39]
	v_lshlrev_b64 v[186:187], 11, v[172:173]
	v_cmp_ne_u32_e64 s[4:5], 1, v182
	v_lshl_add_u64 v[182:183], v[186:187], 0, v[170:171]
	s_andn2_b64 vcc, exec, s[38:39]
	s_waitcnt vmcnt(0)
	s_nop 0
	v_lshlrev_b32_e32 v184, 16, v202
	v_and_b32_e32 v185, 0xffff0000, v202
	v_lshlrev_b32_e32 v192, 16, v203
	v_and_b32_e32 v193, 0xffff0000, v203
	v_lshlrev_b32_e32 v202, 16, v204
	v_and_b32_e32 v203, 0xffff0000, v204
	v_lshlrev_b32_e32 v204, 16, v205
	v_and_b32_e32 v205, 0xffff0000, v205
	v_pk_add_f32 v[136:137], v[136:137], v[192:193]
	v_pk_add_f32 v[134:135], v[134:135], v[184:185]
	v_pk_add_f32 v[132:133], v[132:133], v[204:205]
	v_pk_add_f32 v[130:131], v[130:131], v[202:203]
	v_lshl_add_u64 v[184:185], v[182:183], 2, s[24:25]
	s_cbranch_vccnz .LBB0_583
	global_store_dwordx4 v[184:185], v[134:137], off sc1
	global_store_dwordx4 v[184:185], v[130:133], off offset:16 sc1
.LBB0_583:
	s_and_b64 vcc, exec, s[10:11]
	s_cbranch_vccz .LBB0_585
	v_lshl_add_u64 v[186:187], v[186:187], 1, v[168:169]
	v_cvt_pk_bf16_f32 v202, v134, v135
	v_cvt_pk_bf16_f32 v203, v136, v137
	v_cvt_pk_bf16_f32 v204, v130, v131
	v_cvt_pk_bf16_f32 v205, v132, v133
	global_store_dwordx4 v[186:187], v[202:205], off sc1
.LBB0_585:
	v_lshlrev_b32_e32 v186, 16, v154
	v_and_b32_e32 v187, 0xffff0000, v154
	v_lshlrev_b32_e32 v154, 16, v155
	v_and_b32_e32 v155, 0xffff0000, v155
	v_lshlrev_b32_e32 v192, 16, v156
	v_and_b32_e32 v193, 0xffff0000, v156
	v_lshlrev_b32_e32 v156, 16, v157
	v_and_b32_e32 v157, 0xffff0000, v157
	v_pk_add_f32 v[124:125], v[124:125], v[154:155]
	v_pk_add_f32 v[122:123], v[122:123], v[186:187]
	v_pk_add_f32 v[116:117], v[116:117], v[156:157]
	s_and_b64 vcc, exec, s[4:5]
	v_pk_add_f32 v[114:115], v[114:115], v[192:193]
	s_cbranch_vccnz .LBB0_587
	global_store_dwordx4 v[184:185], v[122:125], off offset:512 sc1
	global_store_dwordx4 v[184:185], v[114:117], off offset:528 sc1
.LBB0_587:
	s_and_b64 vcc, exec, s[10:11]
	s_cbranch_vccz .LBB0_589
	v_lshlrev_b64 v[182:183], 1, v[182:183]
	v_or_b32_e32 v182, 0x100, v182
	v_lshl_add_u64 v[182:183], s[16:17], 0, v[182:183]
	v_cvt_pk_bf16_f32 v154, v122, v123
	v_cvt_pk_bf16_f32 v155, v124, v125
	v_cvt_pk_bf16_f32 v156, v114, v115
	v_cvt_pk_bf16_f32 v157, v116, v117
	global_store_dwordx4 v[182:183], v[154:157], off sc1

.LBB0_591:
	s_or_b64 exec, exec, s[50:51]
	v_lshlrev_b64 v[122:123], 11, v[180:181]
	v_lshlrev_b32_e32 v116, 16, v150
	v_and_b32_e32 v117, 0xffff0000, v150
	v_lshlrev_b32_e32 v130, 16, v151
	v_and_b32_e32 v131, 0xffff0000, v151
	v_lshlrev_b32_e32 v132, 16, v152
	v_and_b32_e32 v133, 0xffff0000, v152
	v_lshlrev_b32_e32 v134, 16, v153
	v_and_b32_e32 v135, 0xffff0000, v153
	s_waitcnt lgkmcnt(0)
	v_lshl_add_u64 v[114:115], v[122:123], 0, v[170:171]
	v_pk_add_f32 v[112:113], v[112:113], v[130:131]
	v_pk_add_f32 v[110:111], v[110:111], v[116:117]
	v_pk_add_f32 v[108:109], v[108:109], v[134:135]
	v_pk_add_f32 v[106:107], v[106:107], v[132:133]
	s_and_b64 vcc, exec, s[4:5]
	v_lshl_add_u64 v[116:117], v[114:115], 2, s[24:25]
	s_cbranch_vccnz .LBB0_593
	global_store_dwordx4 v[116:117], v[110:113], off sc1
	global_store_dwordx4 v[116:117], v[106:109], off offset:16 sc1
.LBB0_593:
	s_and_b64 vcc, exec, s[10:11]
	s_cbranch_vccz .LBB0_595
	v_lshl_add_u64 v[122:123], v[122:123], 1, v[168:169]
	v_cvt_pk_bf16_f32 v130, v110, v111
	v_cvt_pk_bf16_f32 v131, v112, v113
	v_cvt_pk_bf16_f32 v132, v106, v107
	v_cvt_pk_bf16_f32 v133, v108, v109
	global_store_dwordx4 v[122:123], v[130:133], off sc1
.LBB0_595:
	v_lshlrev_b32_e32 v122, 16, v146
	v_and_b32_e32 v123, 0xffff0000, v146
	v_lshlrev_b32_e32 v130, 16, v147
	v_and_b32_e32 v131, 0xffff0000, v147
	v_lshlrev_b32_e32 v132, 16, v148
	v_and_b32_e32 v133, 0xffff0000, v148
	v_lshlrev_b32_e32 v134, 16, v149
	v_and_b32_e32 v135, 0xffff0000, v149
	v_pk_add_f32 v[104:105], v[104:105], v[130:131]
	v_pk_add_f32 v[102:103], v[102:103], v[122:123]
	v_pk_add_f32 v[100:101], v[100:101], v[134:135]
	s_and_b64 vcc, exec, s[4:5]
	v_pk_add_f32 v[98:99], v[98:99], v[132:133]
	s_cbranch_vccnz .LBB0_597
	global_store_dwordx4 v[116:117], v[102:105], off offset:512 sc1
	global_store_dwordx4 v[116:117], v[98:101], off offset:528 sc1
.LBB0_597:
	s_and_b64 vcc, exec, s[10:11]
	s_cbranch_vccz .LBB0_599
	v_lshlrev_b64 v[122:123], 1, v[114:115]
	v_or_b32_e32 v122, 0x100, v122
	v_lshl_add_u64 v[122:123], s[16:17], 0, v[122:123]
	v_cvt_pk_bf16_f32 v114, v102, v103
	v_cvt_pk_bf16_f32 v115, v104, v105
	v_cvt_pk_bf16_f32 v116, v98, v99
	v_cvt_pk_bf16_f32 v117, v100, v101
	global_store_dwordx4 v[122:123], v[114:117], off sc1

.LBB0_601:
	s_or_b64 exec, exec, s[50:51]
	v_lshlrev_b64 v[102:103], 11, v[178:179]
	v_lshlrev_b32_e32 v100, 16, v142
	v_and_b32_e32 v101, 0xffff0000, v142
	v_lshlrev_b32_e32 v104, 16, v143
	v_and_b32_e32 v105, 0xffff0000, v143
	v_lshlrev_b32_e32 v106, 16, v144
	v_and_b32_e32 v107, 0xffff0000, v144
	v_lshlrev_b32_e32 v108, 16, v145
	v_and_b32_e32 v109, 0xffff0000, v145
	s_waitcnt lgkmcnt(0)
	v_lshl_add_u64 v[98:99], v[102:103], 0, v[170:171]
	v_pk_add_f32 v[96:97], v[96:97], v[104:105]
	v_pk_add_f32 v[94:95], v[94:95], v[100:101]
	v_pk_add_f32 v[92:93], v[92:93], v[108:109]
	v_pk_add_f32 v[90:91], v[90:91], v[106:107]
	s_and_b64 vcc, exec, s[4:5]
	v_lshl_add_u64 v[100:101], v[98:99], 2, s[24:25]
	s_cbranch_vccnz .LBB0_603
	global_store_dwordx4 v[100:101], v[94:97], off sc1
	global_store_dwordx4 v[100:101], v[90:93], off offset:16 sc1
.LBB0_603:
	s_and_b64 vcc, exec, s[10:11]
	s_cbranch_vccz .LBB0_605
	v_lshl_add_u64 v[102:103], v[102:103], 1, v[168:169]
	v_cvt_pk_bf16_f32 v104, v94, v95
	v_cvt_pk_bf16_f32 v105, v96, v97
	v_cvt_pk_bf16_f32 v106, v90, v91
	v_cvt_pk_bf16_f32 v107, v92, v93
	global_store_dwordx4 v[102:103], v[104:107], off sc1
.LBB0_605:
	v_lshlrev_b32_e32 v102, 16, v138
	v_and_b32_e32 v103, 0xffff0000, v138
	v_lshlrev_b32_e32 v104, 16, v139
	v_and_b32_e32 v105, 0xffff0000, v139
	v_lshlrev_b32_e32 v106, 16, v140
	v_and_b32_e32 v107, 0xffff0000, v140
	v_lshlrev_b32_e32 v108, 16, v141
	v_and_b32_e32 v109, 0xffff0000, v141
	v_pk_add_f32 v[88:89], v[88:89], v[104:105]
	v_pk_add_f32 v[86:87], v[86:87], v[102:103]
	v_pk_add_f32 v[84:85], v[84:85], v[108:109]
	s_and_b64 vcc, exec, s[4:5]
	v_pk_add_f32 v[82:83], v[82:83], v[106:107]
	s_cbranch_vccnz .LBB0_607
	global_store_dwordx4 v[100:101], v[86:89], off offset:512 sc1
	global_store_dwordx4 v[100:101], v[82:85], off offset:528 sc1
.LBB0_607:
	s_and_b64 vcc, exec, s[10:11]
	s_cbranch_vccz .LBB0_609
	v_lshlrev_b64 v[102:103], 1, v[98:99]
	v_or_b32_e32 v102, 0x100, v102
	v_lshl_add_u64 v[102:103], s[16:17], 0, v[102:103]
	v_cvt_pk_bf16_f32 v98, v86, v87
	v_cvt_pk_bf16_f32 v99, v88, v89
	v_cvt_pk_bf16_f32 v100, v82, v83
	v_cvt_pk_bf16_f32 v101, v84, v85
	global_store_dwordx4 v[102:103], v[98:101], off sc1

.LBB0_611:
	s_or_b64 exec, exec, s[50:51]
	v_lshlrev_b64 v[86:87], 11, v[174:175]
	v_lshlrev_b32_e32 v84, 16, v126
	v_and_b32_e32 v85, 0xffff0000, v126
	v_lshlrev_b32_e32 v88, 16, v127
	v_and_b32_e32 v89, 0xffff0000, v127
	v_lshlrev_b32_e32 v90, 16, v128
	v_and_b32_e32 v91, 0xffff0000, v128
	v_lshlrev_b32_e32 v92, 16, v129
	v_and_b32_e32 v93, 0xffff0000, v129
	s_waitcnt lgkmcnt(0)
	v_lshl_add_u64 v[82:83], v[86:87], 0, v[170:171]
	v_pk_add_f32 v[80:81], v[80:81], v[88:89]
	v_pk_add_f32 v[78:79], v[78:79], v[84:85]
	v_pk_add_f32 v[76:77], v[76:77], v[92:93]
	v_pk_add_f32 v[74:75], v[74:75], v[90:91]
	s_and_b64 vcc, exec, s[4:5]
	v_lshl_add_u64 v[84:85], v[82:83], 2, s[24:25]
	s_cbranch_vccnz .LBB0_613
	global_store_dwordx4 v[84:85], v[78:81], off sc1
	global_store_dwordx4 v[84:85], v[74:77], off offset:16 sc1
.LBB0_613:
	s_and_b64 vcc, exec, s[10:11]
	s_cbranch_vccz .LBB0_615
	v_lshl_add_u64 v[86:87], v[86:87], 1, v[168:169]
	v_cvt_pk_bf16_f32 v88, v78, v79
	v_cvt_pk_bf16_f32 v89, v80, v81
	v_cvt_pk_bf16_f32 v90, v74, v75
	v_cvt_pk_bf16_f32 v91, v76, v77
	global_store_dwordx4 v[86:87], v[88:91], off sc1
.LBB0_615:
	v_lshlrev_b32_e32 v86, 16, v118
	v_and_b32_e32 v87, 0xffff0000, v118
	v_lshlrev_b32_e32 v88, 16, v119
	v_and_b32_e32 v89, 0xffff0000, v119
	v_lshlrev_b32_e32 v90, 16, v120
	v_and_b32_e32 v91, 0xffff0000, v120
	v_lshlrev_b32_e32 v92, 16, v121
	v_and_b32_e32 v93, 0xffff0000, v121
	v_pk_add_f32 v[72:73], v[72:73], v[88:89]
	v_pk_add_f32 v[70:71], v[70:71], v[86:87]
	v_pk_add_f32 v[68:69], v[68:69], v[92:93]
	s_and_b64 vcc, exec, s[4:5]
	v_pk_add_f32 v[66:67], v[66:67], v[90:91]
	s_cbranch_vccnz .LBB0_617
	global_store_dwordx4 v[84:85], v[70:73], off offset:512 sc1
	global_store_dwordx4 v[84:85], v[66:69], off offset:528 sc1
.LBB0_617:
	s_and_b64 vcc, exec, s[10:11]
	s_cbranch_vccz .LBB0_619
	v_lshlrev_b64 v[86:87], 1, v[82:83]
	v_or_b32_e32 v86, 0x100, v86
	v_lshl_add_u64 v[86:87], s[16:17], 0, v[86:87]
	v_cvt_pk_bf16_f32 v82, v70, v71
	v_cvt_pk_bf16_f32 v83, v72, v73
	v_cvt_pk_bf16_f32 v84, v66, v67
	v_cvt_pk_bf16_f32 v85, v68, v69
	global_store_dwordx4 v[86:87], v[82:85], off sc1

.LBB0_621:
	s_or_b64 exec, exec, s[50:51]
	v_add_u32_e32 v100, 0x80, v172
	v_ashrrev_i32_e32 v101, 31, v100
	s_waitcnt lgkmcnt(0)
	v_lshlrev_b64 v[66:67], 12, v[100:101]
	v_add_u32_e32 v98, 0x90, v172
	v_lshl_add_u64 v[66:67], v[168:169], 0, v[66:67]
	v_ashrrev_i32_e32 v99, 31, v98
	global_load_dwordx4 v[108:111], v[66:67], off
	global_load_dwordx4 v[90:93], v[66:67], off offset:256
	v_lshlrev_b64 v[66:67], 12, v[98:99]
	v_add_u32_e32 v96, 0xa0, v172
	v_lshl_add_u64 v[66:67], v[168:169], 0, v[66:67]
	v_ashrrev_i32_e32 v97, 31, v96
	global_load_dwordx4 v[86:89], v[66:67], off
	global_load_dwordx4 v[82:85], v[66:67], off offset:256
	v_lshlrev_b64 v[66:67], 12, v[96:97]
	v_add_u32_e32 v94, 0xb0, v172
	v_lshl_add_u64 v[66:67], v[168:169], 0, v[66:67]
	v_ashrrev_i32_e32 v95, 31, v94
	global_load_dwordx4 v[78:81], v[66:67], off
	global_load_dwordx4 v[74:77], v[66:67], off offset:256
	v_lshlrev_b64 v[66:67], 12, v[94:95]
	v_lshl_add_u64 v[66:67], v[168:169], 0, v[66:67]
	global_load_dwordx4 v[70:73], v[66:67], off
	s_nop 0
	global_load_dwordx4 v[66:69], v[66:67], off offset:256
	v_lshlrev_b64 v[106:107], 11, v[100:101]
	v_lshl_add_u64 v[102:103], v[106:107], 0, v[170:171]
	s_and_b64 vcc, exec, s[4:5]
	s_waitcnt vmcnt(4)
	s_nop 0
	v_lshlrev_b32_e32 v104, 16, v108
	v_and_b32_e32 v105, 0xffff0000, v108
	v_lshlrev_b32_e32 v108, 16, v109
	v_and_b32_e32 v109, 0xffff0000, v109
	v_lshlrev_b32_e32 v112, 16, v110
	v_and_b32_e32 v113, 0xffff0000, v110
	v_lshlrev_b32_e32 v110, 16, v111
	v_and_b32_e32 v111, 0xffff0000, v111
	v_pk_add_f32 v[64:65], v[64:65], v[108:109]
	v_pk_add_f32 v[62:63], v[62:63], v[104:105]
	v_pk_add_f32 v[60:61], v[60:61], v[110:111]
	v_pk_add_f32 v[58:59], v[58:59], v[112:113]
	v_lshl_add_u64 v[104:105], v[102:103], 2, s[24:25]
	s_waitcnt vmcnt(0)
	s_cbranch_vccnz .LBB0_623
	global_store_dwordx4 v[104:105], v[62:65], off sc1
	global_store_dwordx4 v[104:105], v[58:61], off offset:16 sc1
.LBB0_623:
	s_and_b64 vcc, exec, s[10:11]
	s_cbranch_vccz .LBB0_625
	v_lshl_add_u64 v[106:107], v[106:107], 1, v[168:169]
	v_cvt_pk_bf16_f32 v108, v62, v63
	v_cvt_pk_bf16_f32 v109, v64, v65
	v_cvt_pk_bf16_f32 v110, v58, v59
	v_cvt_pk_bf16_f32 v111, v60, v61
	global_store_dwordx4 v[106:107], v[108:111], off sc1
.LBB0_625:
	v_lshlrev_b32_e32 v106, 16, v90
	v_and_b32_e32 v107, 0xffff0000, v90
	v_lshlrev_b32_e32 v90, 16, v91
	v_and_b32_e32 v91, 0xffff0000, v91
	v_lshlrev_b32_e32 v108, 16, v92
	v_and_b32_e32 v109, 0xffff0000, v92
	v_lshlrev_b32_e32 v92, 16, v93
	v_and_b32_e32 v93, 0xffff0000, v93
	v_pk_add_f32 v[56:57], v[56:57], v[90:91]
	v_pk_add_f32 v[54:55], v[54:55], v[106:107]
	v_pk_add_f32 v[52:53], v[52:53], v[92:93]
	s_and_b64 vcc, exec, s[4:5]
	v_pk_add_f32 v[50:51], v[50:51], v[108:109]
	s_cbranch_vccnz .LBB0_627
	global_store_dwordx4 v[104:105], v[54:57], off offset:512 sc1
	global_store_dwordx4 v[104:105], v[50:53], off offset:528 sc1
.LBB0_627:
	s_and_b64 vcc, exec, s[10:11]
	s_cbranch_vccz .LBB0_629
	v_lshlrev_b64 v[102:103], 1, v[102:103]
	v_or_b32_e32 v102, 0x100, v102
	v_lshl_add_u64 v[102:103], s[16:17], 0, v[102:103]
	v_cvt_pk_bf16_f32 v90, v54, v55
	v_cvt_pk_bf16_f32 v91, v56, v57
	v_cvt_pk_bf16_f32 v92, v50, v51
	v_cvt_pk_bf16_f32 v93, v52, v53
	global_store_dwordx4 v[102:103], v[90:93], off sc1

.LBB0_631:
	s_or_b64 exec, exec, s[50:51]
	v_lshlrev_b64 v[54:55], 11, v[98:99]
	v_lshlrev_b32_e32 v52, 16, v86
	v_and_b32_e32 v53, 0xffff0000, v86
	v_lshlrev_b32_e32 v56, 16, v87
	v_and_b32_e32 v57, 0xffff0000, v87
	v_lshlrev_b32_e32 v58, 16, v88
	v_and_b32_e32 v59, 0xffff0000, v88
	v_lshlrev_b32_e32 v60, 16, v89
	v_and_b32_e32 v61, 0xffff0000, v89
	s_waitcnt lgkmcnt(0)
	v_lshl_add_u64 v[50:51], v[54:55], 0, v[170:171]
	v_pk_add_f32 v[48:49], v[48:49], v[56:57]
	v_pk_add_f32 v[46:47], v[46:47], v[52:53]
	v_pk_add_f32 v[44:45], v[44:45], v[60:61]
	v_pk_add_f32 v[42:43], v[42:43], v[58:59]
	s_and_b64 vcc, exec, s[4:5]
	v_lshl_add_u64 v[52:53], v[50:51], 2, s[24:25]
	s_cbranch_vccnz .LBB0_633
	global_store_dwordx4 v[52:53], v[46:49], off sc1
	global_store_dwordx4 v[52:53], v[42:45], off offset:16 sc1
.LBB0_633:
	s_and_b64 vcc, exec, s[10:11]
	s_cbranch_vccz .LBB0_635
	v_lshl_add_u64 v[54:55], v[54:55], 1, v[168:169]
	v_cvt_pk_bf16_f32 v56, v46, v47
	v_cvt_pk_bf16_f32 v57, v48, v49
	v_cvt_pk_bf16_f32 v58, v42, v43
	v_cvt_pk_bf16_f32 v59, v44, v45
	global_store_dwordx4 v[54:55], v[56:59], off sc1
.LBB0_635:
	v_lshlrev_b32_e32 v54, 16, v82
	v_and_b32_e32 v55, 0xffff0000, v82
	v_lshlrev_b32_e32 v56, 16, v83
	v_and_b32_e32 v57, 0xffff0000, v83
	v_lshlrev_b32_e32 v58, 16, v84
	v_and_b32_e32 v59, 0xffff0000, v84
	v_lshlrev_b32_e32 v60, 16, v85
	v_and_b32_e32 v61, 0xffff0000, v85
	v_pk_add_f32 v[40:41], v[40:41], v[56:57]
	v_pk_add_f32 v[38:39], v[38:39], v[54:55]
	v_pk_add_f32 v[36:37], v[36:37], v[60:61]
	s_and_b64 vcc, exec, s[4:5]
	v_pk_add_f32 v[34:35], v[34:35], v[58:59]
	s_cbranch_vccnz .LBB0_637
	global_store_dwordx4 v[52:53], v[38:41], off offset:512 sc1
	global_store_dwordx4 v[52:53], v[34:37], off offset:528 sc1
.LBB0_637:
	s_and_b64 vcc, exec, s[10:11]
	s_cbranch_vccz .LBB0_639
	v_lshlrev_b64 v[54:55], 1, v[50:51]
	v_or_b32_e32 v54, 0x100, v54
	v_lshl_add_u64 v[54:55], s[16:17], 0, v[54:55]
	v_cvt_pk_bf16_f32 v50, v38, v39
	v_cvt_pk_bf16_f32 v51, v40, v41
	v_cvt_pk_bf16_f32 v52, v34, v35
	v_cvt_pk_bf16_f32 v53, v36, v37
	global_store_dwordx4 v[54:55], v[50:53], off sc1

.LBB0_641:
	s_or_b64 exec, exec, s[50:51]
	v_lshlrev_b64 v[38:39], 11, v[96:97]
	v_lshlrev_b32_e32 v36, 16, v78
	v_and_b32_e32 v37, 0xffff0000, v78
	v_lshlrev_b32_e32 v40, 16, v79
	v_and_b32_e32 v41, 0xffff0000, v79
	v_lshlrev_b32_e32 v42, 16, v80
	v_and_b32_e32 v43, 0xffff0000, v80
	v_lshlrev_b32_e32 v44, 16, v81
	v_and_b32_e32 v45, 0xffff0000, v81
	s_waitcnt lgkmcnt(0)
	v_lshl_add_u64 v[34:35], v[38:39], 0, v[170:171]
	v_pk_add_f32 v[32:33], v[32:33], v[40:41]
	v_pk_add_f32 v[30:31], v[30:31], v[36:37]
	v_pk_add_f32 v[28:29], v[28:29], v[44:45]
	v_pk_add_f32 v[26:27], v[26:27], v[42:43]
	s_and_b64 vcc, exec, s[4:5]
	v_lshl_add_u64 v[36:37], v[34:35], 2, s[24:25]
	s_cbranch_vccnz .LBB0_643
	global_store_dwordx4 v[36:37], v[30:33], off sc1
	global_store_dwordx4 v[36:37], v[26:29], off offset:16 sc1
.LBB0_643:
	s_and_b64 vcc, exec, s[10:11]
	s_cbranch_vccz .LBB0_645
	v_lshl_add_u64 v[38:39], v[38:39], 1, v[168:169]
	v_cvt_pk_bf16_f32 v40, v30, v31
	v_cvt_pk_bf16_f32 v41, v32, v33
	v_cvt_pk_bf16_f32 v42, v26, v27
	v_cvt_pk_bf16_f32 v43, v28, v29
	global_store_dwordx4 v[38:39], v[40:43], off sc1
.LBB0_645:
	v_lshlrev_b32_e32 v38, 16, v74
	v_and_b32_e32 v39, 0xffff0000, v74
	v_lshlrev_b32_e32 v40, 16, v75
	v_and_b32_e32 v41, 0xffff0000, v75
	v_lshlrev_b32_e32 v42, 16, v76
	v_and_b32_e32 v43, 0xffff0000, v76
	v_lshlrev_b32_e32 v44, 16, v77
	v_and_b32_e32 v45, 0xffff0000, v77
	v_pk_add_f32 v[24:25], v[24:25], v[40:41]
	v_pk_add_f32 v[22:23], v[22:23], v[38:39]
	v_pk_add_f32 v[20:21], v[20:21], v[44:45]
	s_and_b64 vcc, exec, s[4:5]
	v_pk_add_f32 v[18:19], v[18:19], v[42:43]
	s_cbranch_vccnz .LBB0_647
	global_store_dwordx4 v[36:37], v[22:25], off offset:512 sc1
	global_store_dwordx4 v[36:37], v[18:21], off offset:528 sc1
.LBB0_647:
	s_and_b64 vcc, exec, s[10:11]
	s_cbranch_vccz .LBB0_649
	v_lshlrev_b64 v[38:39], 1, v[34:35]
	v_or_b32_e32 v38, 0x100, v38
	v_lshl_add_u64 v[38:39], s[16:17], 0, v[38:39]
	v_cvt_pk_bf16_f32 v34, v22, v23
	v_cvt_pk_bf16_f32 v35, v24, v25
	v_cvt_pk_bf16_f32 v36, v18, v19
	v_cvt_pk_bf16_f32 v37, v20, v21
	global_store_dwordx4 v[38:39], v[34:37], off sc1

.LBB0_651:
	s_or_b64 exec, exec, s[50:51]
	v_lshlrev_b64 v[22:23], 11, v[94:95]
	v_lshlrev_b32_e32 v20, 16, v70
	v_and_b32_e32 v21, 0xffff0000, v70
	v_lshlrev_b32_e32 v24, 16, v71
	v_and_b32_e32 v25, 0xffff0000, v71
	v_lshlrev_b32_e32 v26, 16, v72
	v_and_b32_e32 v27, 0xffff0000, v72
	v_lshlrev_b32_e32 v28, 16, v73
	v_and_b32_e32 v29, 0xffff0000, v73
	s_waitcnt lgkmcnt(0)
	v_lshl_add_u64 v[18:19], v[22:23], 0, v[170:171]
	v_pk_add_f32 v[16:17], v[16:17], v[24:25]
	v_pk_add_f32 v[14:15], v[14:15], v[20:21]
	v_pk_add_f32 v[12:13], v[12:13], v[28:29]
	v_pk_add_f32 v[10:11], v[10:11], v[26:27]
	s_and_b64 vcc, exec, s[4:5]
	v_lshl_add_u64 v[20:21], v[18:19], 2, s[24:25]
	s_cbranch_vccnz .LBB0_653
	global_store_dwordx4 v[20:21], v[14:17], off sc1
	global_store_dwordx4 v[20:21], v[10:13], off offset:16 sc1
.LBB0_653:
	s_and_b64 vcc, exec, s[10:11]
	s_cbranch_vccz .LBB0_655
	v_lshl_add_u64 v[22:23], v[22:23], 1, v[168:169]
	v_cvt_pk_bf16_f32 v24, v14, v15
	v_cvt_pk_bf16_f32 v25, v16, v17
	v_cvt_pk_bf16_f32 v26, v10, v11
	v_cvt_pk_bf16_f32 v27, v12, v13
	global_store_dwordx4 v[22:23], v[24:27], off sc1
.LBB0_655:
	v_lshlrev_b32_e32 v22, 16, v66
	v_and_b32_e32 v23, 0xffff0000, v66
	v_lshlrev_b32_e32 v24, 16, v67
	v_and_b32_e32 v25, 0xffff0000, v67
	v_lshlrev_b32_e32 v26, 16, v68
	v_and_b32_e32 v27, 0xffff0000, v68
	v_lshlrev_b32_e32 v28, 16, v69
	v_and_b32_e32 v29, 0xffff0000, v69
	v_pk_add_f32 v[8:9], v[8:9], v[24:25]
	v_pk_add_f32 v[6:7], v[6:7], v[22:23]
	v_pk_add_f32 v[4:5], v[4:5], v[28:29]
	s_and_b64 vcc, exec, s[4:5]
	v_pk_add_f32 v[2:3], v[2:3], v[26:27]
	s_cbranch_vccnz .LBB0_657
	global_store_dwordx4 v[20:21], v[6:9], off offset:512 sc1
	global_store_dwordx4 v[20:21], v[2:5], off offset:528 sc1
.LBB0_657:
	s_and_b64 vcc, exec, s[10:11]
	s_cbranch_vccz .LBB0_659
	v_lshlrev_b64 v[22:23], 1, v[18:19]
	v_or_b32_e32 v22, 0x100, v22
	v_lshl_add_u64 v[22:23], s[16:17], 0, v[22:23]
	v_cvt_pk_bf16_f32 v18, v6, v7
	v_cvt_pk_bf16_f32 v19, v8, v9
	v_cvt_pk_bf16_f32 v20, v2, v3
	v_cvt_pk_bf16_f32 v21, v4, v5
	global_store_dwordx4 v[22:23], v[18:21], off sc1
